# attention phases: static s_setprio 1 for waves 4-7 (reset to 0 at phase end), on top of previous
# baseline (speedup 1.0000x reference)
; #define LAS __attribute__((address_space(3)))
; DI int get_tid() { int t = threadIdx.x; asm volatile("" : "+v"(t)); return t; }
; DI void diff_item(const Params& P, char* lds, int layer, int pair, int qt, int& tab_head) {
;     ...
;         const float lam = ((const float*)(P.ws + WS_LAM))[layer];
;         const float lam_init = 0.8f - 0.6f * expf(-0.3f * (float)layer);
; DI void phase_att(const Params& P, char* lds, int hb, int layer) {
;     unsigned* ctr = (unsigned*)(P.ws + WS_CTR) + (hb * 2 + layer) * 8;
;     LAS int* slot = (LAS int*)(lds + LDS_SLOT);
;     const int tid = get_tid();
;     constexpr int NQ = 64 + 384;
;     int tab_head = -1;
.LBB0_194:
	s_or_b64 exec, exec, s[0:1]
	v_writelane_b32 v236, s72, 46
	s_xor_b64 s[0:1], s[72:73], -1
	s_mov_b64 s[2:3], s[24:25]
	v_writelane_b32 v236, s73, 47
	v_readlane_b32 s20, v237, 12
	v_writelane_b32 v236, s0, 48
	v_readlane_b32 s21, v237, 13
	s_mov_b64 s[10:11], s[38:39]
	v_writelane_b32 v236, s1, 49
	s_mov_b64 s[4:5], s[98:99]
	s_mov_b64 s[6:7], s[28:29]
	s_mov_b64 s[30:31], s[20:21]
	s_mov_b64 s[0:1], s[60:61]
	v_mov_b32_e32 v0, v174
	s_waitcnt lgkmcnt(0)
	s_barrier
	v_readfirstlane_b32 s2, v174
	s_nop 3
	s_bitcmp1_b32 s2, 8
	s_cbranch_scc0 .Latt_noprio
	s_setprio 1
.Latt_noprio:
	s_lshl_b32 s2, s96, 3
	v_cmp_eq_u32_e64 s[36:37], 0, v0
	v_cvt_f32_u32_e32 v0, s96
	v_readlane_b32 s3, v236, 42
	s_or_b32 s16, s2, s3
	s_lshl_b64 s[2:3], s[16:17], 2
	v_mul_f32_e32 v0, 0xbe99999a, v0
	s_add_u32 s98, s0, s2
	v_mul_f32_e32 v2, 0x3fb8aa3b, v0
	s_mov_b32 s2, 0x3fb8aa3b
	v_fma_f32 v3, v0, s2, -v2
	v_rndne_f32_e32 v4, v2
	v_fmac_f32_e32 v3, 0x32a5705f, v0
	v_sub_f32_e32 v2, v2, v4
	s_addc_u32 s99, s1, s3
	v_add_f32_e32 v2, v2, v3
	s_lshl_b32 s16, s96, 7
	v_exp_f32_e32 v2, v2
	v_cvt_i32_f32_e32 v3, v4
	s_add_u32 s34, s0, 0xcf40000
	s_addc_u32 s35, s1, 0
	s_add_u32 s4, s0, 0xcd00000
	s_mov_b32 s2, 0xc2ce8ed0
	s_addc_u32 s5, s1, 0
	v_ldexp_f32 v2, v2, v3
	v_cmp_ngt_f32_e32 vcc, s2, v0
	s_mov_b32 s2, 0x42b17218
	s_add_u32 s6, s0, 0x8500000
	v_cndmask_b32_e32 v2, 0, v2, vcc
	v_cmp_nlt_f32_e32 vcc, s2, v0
	s_addc_u32 s7, s1, 0
	s_mov_b32 s2, s96
	s_mov_b32 s97, s17
	s_add_u32 s46, s0, 0x32000
	v_writelane_b32 v236, s2, 50
	s_addc_u32 s47, s1, 0
	v_cndmask_b32_e32 v0, v187, v2, vcc
	v_writelane_b32 v236, s3, 51
	s_lshl_b64 s[2:3], s[96:97], 2
	s_add_u32 s2, s0, s2
	s_addc_u32 s3, s1, s3
	s_add_u32 s8, s2, 0x1b000
	s_addc_u32 s9, s3, 0
	s_lshl_b64 s[2:3], s[16:17], 2
	s_add_u32 s10, s10, s2
	s_addc_u32 s11, s11, s3
	v_readlane_b32 s26, v237, 18
	v_readlane_b32 s27, v237, 19
	v_fmamk_f32 v0, v0, 0x3f19999a, v177
	s_add_u32 s12, s0, 0x20000
	s_mov_b32 s26, 0
	s_mul_i32 s27, s96, 12
	v_add_f32_e32 v192, 1.0, v0
	s_addc_u32 s13, s1, 0
	s_mov_b32 s49, -1
	s_mov_b32 s2, s33
	v_readlane_b32 s22, v237, 14
	v_readlane_b32 s23, v237, 15
	v_readlane_b32 s24, v237, 16
	v_readlane_b32 s25, v237, 17
	s_branch .LBB0_196

; DI unsigned xb_add(unsigned* p, unsigned v) { return __hip_atomic_fetch_add(p, v, __ATOMIC_RELAXED, __HIP_MEMORY_SCOPE_AGENT); }
; DI void xcd_barrier(const XcdBarrier& b) {
;     asm volatile("s_waitcnt vmcnt(0)" ::: "memory");
;     __syncthreads();
;     if (threadIdx.x == 0) {
;         unsigned* bar = b.bar;
;         __builtin_amdgcn_s_waitcnt(0);
;         unsigned nloc = b.st[0], nx = b.st[1];
;         if (nloc == 0u) { xcd_barrier_complete(bar, b.x, nloc, nx); b.st[0] = nloc; b.st[1] = nx; }
;         const unsigned old = xb_add(&bar[XB_XSUB(b.x)], 1u);
;         const unsigned gen = old / nloc;
;         if (old + 1u == (gen + 1u) * nloc) {
.LBB0_270:
	s_setprio 0
	s_waitcnt vmcnt(0)
	s_waitcnt lgkmcnt(0)
	s_barrier
	s_mov_b64 s[0:1], exec
	v_readlane_b32 s24, v237, 4
	v_readlane_b32 s36, v237, 0
	v_readlane_b32 s64, v236, 34
	v_readlane_b32 s26, v237, 6
	v_readlane_b32 s27, v237, 7
	v_readlane_b32 s30, v237, 10
	v_readlane_b32 s31, v237, 11
	v_readlane_b32 s37, v237, 1
	v_readlane_b32 s65, v236, 35
	v_readlane_b32 s98, v236, 36
	v_readlane_b32 s22, v236, 22
	v_readlane_b32 s34, v236, 24
	v_readlane_b32 s36, v236, 26
	v_readlane_b32 s26, v236, 28
	v_readlane_b32 s30, v236, 30
	v_readlane_b32 s20, v236, 32
	s_and_b64 s[2:3], s[0:1], s[64:65]
	v_readlane_b32 s25, v237, 5
	v_readlane_b32 s28, v237, 8
	v_readlane_b32 s29, v237, 9
	v_readlane_b32 s38, v237, 2
	v_readlane_b32 s39, v237, 3
	v_readlane_b32 s99, v236, 37
	v_readlane_b32 s58, v236, 21
	v_readlane_b32 s23, v236, 23
	v_readlane_b32 s35, v236, 25
	v_readlane_b32 s37, v236, 27
	v_readlane_b32 s27, v236, 29
	v_readlane_b32 s31, v236, 31
	v_readlane_b32 s21, v236, 33
	v_readlane_b32 s16, v236, 2
	v_readlane_b32 s63, v236, 38
	v_readlane_b32 s70, v236, 39
	s_mov_b32 s40, 0x180000
	v_readlane_b32 s96, v236, 50
	v_readlane_b32 s97, v236, 51
	s_mov_b64 exec, s[2:3]
	s_cbranch_execz .LBB0_322
	v_mov_b32_e32 v0, s63
	s_waitcnt vmcnt(0) expcnt(0) lgkmcnt(0)
	ds_read_b32 v3, v0
	v_mov_b32_e32 v0, s70
	ds_read_b32 v2, v0
	s_waitcnt lgkmcnt(1)
	v_cmp_ne_u32_e32 vcc, 0, v3
	s_cbranch_vccnz .LBB0_286
	s_mov_b32 s2, 1
	s_branch .LBB0_274
